# attention: K-fragment LDS reads issued ahead of the next tile's LDS-DMA issue block so their latency runs under it
# baseline (speedup 1.0000x reference)
.LBB0_95:
	s_mov_b32 s3, 1
	s_branch .Lkv_a
.LBB0_96:
	s_mov_b32 s3, 0
.Lkv_a:
	s_and_b32 s41, s2, 1
	v_lshl_or_b32 v0, s41, 13, v204
	v_add_u32_e32 v1, v0, v205
	v_add_u32_e32 v222, v0, v206
	v_add_u32_e32 v223, v0, v207
	v_add_u32_e32 v0, v0, v208
	ds_read_b128 v[4:7], v1
	ds_read_b128 v[8:11], v1 offset:4096
	ds_read_b128 v[12:15], v222
	ds_read_b128 v[112:115], v222 offset:4096
	ds_read_b128 v[116:119], v223
	ds_read_b128 v[120:123], v223 offset:4096
	ds_read_b128 v[124:127], v0
	ds_read_b128 v[218:221], v0 offset:4096
	s_cmp_eq_u32 s3, 0
	s_cbranch_scc1 .Lnd_a
	s_and_b32 s59, s40, 1
	s_lshl_b32 s59, s59, 13
	s_add_u32 s59, s59, s76
	s_mov_b32 m0, s59
	s_add_u32 s59, s59, 0x400
	global_load_lds_dwordx4 v226, s[44:45]
	s_mov_b32 m0, s59
	s_and_b32 s59, s40, 1
	s_lshl_b32 s59, s59, 14
	global_load_lds_dwordx4 v227, s[44:45]
	s_add_u32 s59, s59, s77
	s_mov_b32 m0, s59
	s_add_u32 s59, s59, 0x400
	global_load_lds_dwordx4 v228, s[46:47]
	s_mov_b32 m0, s59
	s_add_u32 s59, s59, 0x400
	global_load_lds_dwordx4 v229, s[46:47]
	s_mov_b32 m0, s59
	s_add_u32 s59, s59, 0x400
	global_load_lds_dwordx4 v228, s[48:49]
	s_mov_b32 m0, s59
	s_add_u32 s44, s44, 0x74000
	global_load_lds_dwordx4 v229, s[48:49]
	s_addc_u32 s45, s45, 0
	s_add_u32 s46, s46, 0x80
	s_addc_u32 s47, s47, 0
	s_add_u32 s48, s48, 0x80
	s_addc_u32 s49, s49, 0
.Lnd_a:
	s_add_i32 s42, s2, 4
	s_mov_b64 s[2:3], -1
	s_cmp_lt_u32 s42, s20
	s_waitcnt lgkmcnt(7)
	v_mfma_f32_32x32x16_bf16 v[96:111], v[4:7], v[128:131], 0
	s_waitcnt lgkmcnt(6)
	v_mfma_f32_32x32x16_bf16 v[80:95], v[8:11], v[128:131], 0
	s_waitcnt lgkmcnt(5)
	v_mfma_f32_32x32x16_bf16 v[96:111], v[12:15], v[132:135], v[96:111]
	s_waitcnt lgkmcnt(4)
	v_mfma_f32_32x32x16_bf16 v[80:95], v[112:115], v[132:135], v[80:95]
	s_waitcnt lgkmcnt(3)
	v_mfma_f32_32x32x16_bf16 v[96:111], v[116:119], v[136:139], v[96:111]
	s_waitcnt lgkmcnt(2)
	v_mfma_f32_32x32x16_bf16 v[80:95], v[120:123], v[136:139], v[80:95]
	s_waitcnt lgkmcnt(1)
	v_mfma_f32_32x32x16_bf16 v[96:111], v[124:127], v[140:143], v[96:111]
	s_waitcnt lgkmcnt(0)
	v_mfma_f32_32x32x16_bf16 v[80:95], v[218:221], v[140:143], v[80:95]
	s_cbranch_scc0 .LBB0_102
	s_andn2_b64 vcc, exec, s[2:3]
	s_cbranch_vccz .LBB0_103

.Lkv_b:
	s_and_b32 s40, s2, 1
	v_lshl_or_b32 v0, s40, 13, v204
	v_add_u32_e32 v1, v0, v205
	v_add_u32_e32 v163, v0, v206
	v_add_u32_e32 v167, v0, v207
	v_add_u32_e32 v0, v0, v208
	ds_read_b128 v[100:103], v1
	ds_read_b128 v[108:111], v163
	ds_read_b128 v[116:119], v167
	ds_read_b128 v[124:127], v0
	ds_read_b128 v[104:107], v1 offset:4096
	ds_read_b128 v[112:115], v163 offset:4096
	ds_read_b128 v[120:123], v167 offset:4096
	ds_read_b128 v[170:173], v0 offset:4096
	s_cmp_eq_u32 s3, 0
	s_cbranch_scc1 .Lnd_b
	s_and_b32 s59, s21, 1
	s_lshl_b32 s59, s59, 13
	s_add_u32 s59, s59, s76
	s_mov_b32 m0, s59
	s_add_u32 s59, s59, 0x400
	global_load_lds_dwordx4 v226, s[44:45]
	s_mov_b32 m0, s59
	s_and_b32 s59, s21, 1
	s_lshl_b32 s59, s59, 14
	global_load_lds_dwordx4 v227, s[44:45]
	s_add_u32 s59, s59, s77
	s_mov_b32 m0, s59
	s_add_u32 s59, s59, 0x400
	global_load_lds_dwordx4 v228, s[46:47]
	s_mov_b32 m0, s59
	s_add_u32 s59, s59, 0x400
	global_load_lds_dwordx4 v229, s[46:47]
	s_mov_b32 m0, s59
	s_add_u32 s59, s59, 0x400
	global_load_lds_dwordx4 v228, s[48:49]
	s_mov_b32 m0, s59
	s_add_u32 s44, s44, 0x74000
	global_load_lds_dwordx4 v229, s[48:49]
	s_addc_u32 s45, s45, 0
	s_add_u32 s46, s46, 0x80
	s_addc_u32 s47, s47, 0
	s_add_u32 s48, s48, 0x80
	s_addc_u32 s49, s49, 0
.Lnd_b:
	s_add_i32 s41, s2, 4
	s_mov_b64 s[2:3], -1
	s_cmp_lt_u32 s41, s20
	s_waitcnt lgkmcnt(7)
	v_mfma_f32_32x32x16_bf16 v[84:99], v[100:103], v[128:131], 0
	s_waitcnt lgkmcnt(6)
	v_mfma_f32_32x32x16_bf16 v[84:99], v[108:111], v[132:135], v[84:99]
	s_waitcnt lgkmcnt(5)
	v_mfma_f32_32x32x16_bf16 v[84:99], v[116:119], v[136:139], v[84:99]
	s_waitcnt lgkmcnt(4)
	v_mfma_f32_32x32x16_bf16 v[84:99], v[124:127], v[140:143], v[84:99]
	s_waitcnt lgkmcnt(3)
	v_mfma_f32_32x32x16_bf16 v[68:83], v[104:107], v[128:131], 0
	s_waitcnt lgkmcnt(2)
	v_mfma_f32_32x32x16_bf16 v[68:83], v[112:115], v[132:135], v[68:83]
	s_waitcnt lgkmcnt(1)
	v_mfma_f32_32x32x16_bf16 v[68:83], v[120:123], v[136:139], v[68:83]
	s_waitcnt lgkmcnt(0)
	v_mfma_f32_32x32x16_bf16 v[68:83], v[170:173], v[140:143], v[68:83]
	s_cbranch_scc0 .LBB0_112
	s_andn2_b64 vcc, exec, s[2:3]
	s_cbranch_vccz .LBB0_113
